# mixer A masked tiles: visibility mask = one unsigned compare per element (dist <u limit) instead of three compares plus scalar combines
# speedup vs baseline: 1.0120x; 1.0120x over previous
; template <bool MASKED>
; DI bool attnA_tile_math(const f32x16& Su, const LAS float* bt, int qpos, int kpos0, int kvalid, bool meta_tile, int h, int lane, float& m, float& l, float& corr, bf16x8 (&bfrag)[2]) {
;     ...
;         const int row = (r & 3) + 8 * (r >> 2) + 4 * h;
;         const int dist = qpos - (kpos0 + row);
;         if (MASKED) {
;             const bool vis = (row < kvalid) && (dist >= 0) && (meta_tile || dist < 128);
;             const int di = dist < 0 ? 0 : (dist > 128 ? 128 : dist);
;             const float v = Su[r] * (0.125f * 1.4426950408889634f) + bt[di];
;             sc[r] = vis ? v : -1e30f;
.LBB0_197:
	s_lshl_b32 s4, s31, 5
	s_or_b32 s6, s4, 16
	s_cmp_lt_i32 s31, 0
	s_cselect_b64 s[8:9], -1, 0
	s_and_b64 s[4:5], s[8:9], exec
	s_cselect_b32 s30, 16, 32
	s_cselect_b32 s42, 0, s6
	s_or_b32 s4, s31, s28
	s_cmp_lt_i32 s4, 0
	s_cselect_b64 s[4:5], -1, 0
	s_cmp_le_i32 s31, s86
	v_add_u32_e32 v211, s42, v125
	s_cselect_b64 s[6:7], -1, 0
	s_cmp_ge_i32 s31, s28
	v_sub_u32_e32 v186, v128, v211
	s_cselect_b64 s[10:11], -1, 0
	s_or_b64 s[4:5], s[6:7], s[4:5]
	v_cmp_gt_i32_e32 vcc, s30, v125
	v_cmp_lt_i32_e64 s[36:37], -1, v186
	v_add_u32_e32 v66, s42, v130
	s_or_b64 s[6:7], s[4:5], s[10:11]
	s_cbranch_scc0 .LfastA
	s_and_b64 s[4:5], s[8:9], exec
	s_cselect_b32 s4, 0x80000000, s15
	s_cselect_b32 s5, 0, s15
	ds_read_b128 v[66:69], v129 offset:6144
	ds_read_b128 v[120:123], v129 offset:7168
	ds_read_b128 v[168:171], v129 offset:8192
	ds_read_b128 v[178:181], v129 offset:9216
	v_cmp_gt_u32_e64 s[36:37], s4, v186
	v_med3_i32 v0, v186, 0, v176
	v_add_u32_e32 v173, -1, v186
	v_cmp_gt_u32_e64 s[38:39], s4, v173
	v_med3_i32 v173, v173, 0, v176
	v_add_u32_e32 v182, -2, v186
	v_cmp_gt_u32_e64 s[40:41], s4, v182
	v_med3_i32 v182, v182, 0, v176
	v_add_u32_e32 v183, -3, v186
	v_cmp_gt_u32_e64 s[44:45], s4, v183
	v_med3_i32 v183, v183, 0, v176
	v_sub_u32_e32 v184, v147, v211
	v_cmp_gt_u32_e64 s[48:49], s4, v184
	v_med3_i32 v184, v184, 0, v176
	v_sub_u32_e32 v185, v148, v211
	v_cmp_gt_u32_e64 s[52:53], s4, v185
	v_med3_i32 v185, v185, 0, v176
	v_sub_u32_e32 v187, v149, v211
	v_cmp_gt_u32_e64 s[56:57], s4, v187
	v_med3_i32 v187, v187, 0, v176
	v_sub_u32_e32 v188, v150, v211
	v_cmp_gt_u32_e64 s[60:61], s4, v188
	v_med3_i32 v188, v188, 0, v176
	v_sub_u32_e32 v189, v151, v211
	v_cmp_gt_u32_e64 s[42:43], s5, v189
	v_med3_i32 v189, v189, 0, v176
	v_sub_u32_e32 v190, v152, v211
	v_cmp_gt_u32_e64 s[46:47], s5, v190
	v_med3_i32 v190, v190, 0, v176
	v_sub_u32_e32 v191, v153, v211
	v_cmp_gt_u32_e64 s[50:51], s5, v191
	v_med3_i32 v191, v191, 0, v176
	v_sub_u32_e32 v192, v158, v211
	v_cmp_gt_u32_e64 s[54:55], s5, v192
	v_med3_i32 v192, v192, 0, v176
	v_sub_u32_e32 v205, v159, v211
	v_cmp_gt_u32_e64 s[58:59], s5, v205
	v_med3_i32 v205, v205, 0, v176
	v_sub_u32_e32 v215, v160, v211
	v_cmp_gt_u32_e64 s[62:63], s5, v215
	v_med3_i32 v215, v215, 0, v176
	v_sub_u32_e32 v216, v161, v211
	v_cmp_gt_u32_e64 s[64:65], s5, v216
	v_med3_i32 v216, v216, 0, v176
	v_sub_u32_e32 v217, v162, v211
	v_cmp_gt_u32_e64 s[66:67], s5, v217
	v_med3_i32 v217, v217, 0, v176
	s_waitcnt lgkmcnt(0)
